# G1/G3 K-loop: next-iteration DMA pointer SALU block hoisted in front of the head barrier (on top of v23 back-edge rotation)
# baseline (speedup 1.0000x reference)
; template <class Epi, class Sched, bool ALIGN_EPI = false, bool SP2 = false>
; __device__ __forceinline__ void gemm_phase(PG8_LAS unsigned char* lds, const Gemm g, const Sched& S, const Epi& E) {
;     ...
;     f32x4 acc[2][2][4][2];
; #pragma unroll
;     for (int a = 0; a < 2; ++a)
; #pragma unroll
;         for (int b = 0; b < 2; ++b)
; #pragma unroll
;             for (int m = 0; m < 4; ++m)
; #pragma unroll
;                 for (int n = 0; n < 2; ++n) acc[a][b][m][n] = (f32x4){0.f, 0.f, 0.f, 0.f};
;     bf16x8 At[4][2], B0[2][2], B1[2][2];
;     const char* cA = (const char*)g.A + (size_t)cur.pm * tstep; const char* cB = (const char*)g.Bt + (size_t)cur.pn * tstep;
;     ...
;         const char* nA = has_next ? (const char*)g.A + (size_t)nxt.pm * tstep : cA; const char* nB = has_next ? (const char*)g.Bt + (size_t)nxt.pn * tstep : cB;
;         for (int t = 0; t < nt; t += 2) {
;             const bool last = (t == nt - 2);
;             const char* a1 = cA + (size_t)(t + 1) * kstep;
;             const char* a2 = last ? nA : cA + (size_t)(t + 2) * kstep; const char* b2 = last ? nB : cB + (size_t)(t + 2) * kstep;
;             const char* a3 = a2 + kstep; const char* b3 = b2 + kstep;
.LBB0_37:
	s_ashr_i32 s55, s54, 31
	s_lshl_b64 s[2:3], s[54:55], 20
	s_add_u32 s56, s46, s2
	s_addc_u32 s57, s47, s3
	s_and_b64 s[2:3], s[40:41], exec
	s_cselect_b32 s2, s57, s63
	s_cselect_b32 s3, s56, s62
	s_ashr_i32 s53, s52, 31
	s_lshl_b64 s[58:59], s[52:53], 20
	s_add_u32 s58, s66, s58
	s_addc_u32 s59, s67, s59
	s_mov_b32 s95, s65
	s_and_b64 s[64:65], s[40:41], exec
	s_cselect_b32 s53, s59, s61
	s_cselect_b32 s55, s58, s60
	s_add_u32 s79, s60, 0x100
	s_addc_u32 s82, s61, 0
	s_add_u32 s60, s62, 0x80080
	v_mov_b32_e32 v2, 0
	s_addc_u32 s61, s63, 0
	s_mov_b32 s83, -2
	v_mov_b32_e32 v3, v2
	v_mov_b32_e32 v4, v2
	v_mov_b32_e32 v5, v2
	v_mov_b32_e32 v6, v2
	s_waitcnt lgkmcnt(0)
	v_mov_b32_e32 v7, v2
	v_mov_b32_e32 v8, v2
	v_mov_b32_e32 v9, v2
	v_mov_b32_e32 v18, v2
	v_mov_b32_e32 v19, v2
	v_mov_b32_e32 v20, v2
	v_mov_b32_e32 v21, v2
	v_mov_b32_e32 v22, v2
	v_mov_b32_e32 v23, v2
	v_mov_b32_e32 v24, v2
	v_mov_b32_e32 v25, v2
	v_mov_b32_e32 v34, v2
	v_mov_b32_e32 v35, v2
	v_mov_b32_e32 v36, v2
	v_mov_b32_e32 v37, v2
	v_mov_b32_e32 v38, v2
	v_mov_b32_e32 v39, v2
	v_mov_b32_e32 v40, v2
	v_mov_b32_e32 v41, v2
	v_mov_b32_e32 v50, v2
	v_mov_b32_e32 v51, v2
	v_mov_b32_e32 v52, v2
	v_mov_b32_e32 v53, v2
	v_mov_b32_e32 v54, v2
	v_mov_b32_e32 v55, v2
	v_mov_b32_e32 v56, v2
	v_mov_b32_e32 v57, v2
	v_mov_b32_e32 v10, v2
	v_mov_b32_e32 v11, v2
	v_mov_b32_e32 v12, v2
	v_mov_b32_e32 v13, v2
	v_mov_b32_e32 v14, v2
	v_mov_b32_e32 v15, v2
	v_mov_b32_e32 v16, v2
	v_mov_b32_e32 v17, v2
	v_mov_b32_e32 v26, v2
	v_mov_b32_e32 v27, v2
	v_mov_b32_e32 v28, v2
	v_mov_b32_e32 v29, v2
	v_mov_b32_e32 v30, v2
	v_mov_b32_e32 v31, v2
	v_mov_b32_e32 v32, v2
	v_mov_b32_e32 v33, v2
	v_mov_b32_e32 v42, v2
	v_mov_b32_e32 v43, v2
	v_mov_b32_e32 v44, v2
	v_mov_b32_e32 v45, v2
	v_mov_b32_e32 v46, v2
	v_mov_b32_e32 v47, v2
	v_mov_b32_e32 v48, v2
	v_mov_b32_e32 v49, v2
	v_mov_b32_e32 v58, v2
	v_mov_b32_e32 v59, v2
	v_mov_b32_e32 v60, v2
	v_mov_b32_e32 v61, v2
	v_mov_b32_e32 v62, v2
	v_mov_b32_e32 v63, v2
	v_mov_b32_e32 v64, v2
	v_mov_b32_e32 v65, v2
	v_mov_b32_e32 v66, v2
	v_mov_b32_e32 v67, v2
	v_mov_b32_e32 v68, v2
	v_mov_b32_e32 v69, v2
	v_mov_b32_e32 v70, v2
	v_mov_b32_e32 v71, v2
	v_mov_b32_e32 v72, v2
	v_mov_b32_e32 v73, v2
	v_mov_b32_e32 v82, v2
	v_mov_b32_e32 v83, v2
	v_mov_b32_e32 v84, v2
	v_mov_b32_e32 v85, v2
	v_mov_b32_e32 v86, v2
	v_mov_b32_e32 v87, v2
	v_mov_b32_e32 v88, v2
	v_mov_b32_e32 v89, v2
	v_mov_b32_e32 v98, v2
	v_mov_b32_e32 v99, v2
	v_mov_b32_e32 v100, v2
	v_mov_b32_e32 v101, v2
	v_mov_b32_e32 v102, v2
	v_mov_b32_e32 v103, v2
	v_mov_b32_e32 v104, v2
	v_mov_b32_e32 v105, v2
	v_mov_b32_e32 v114, v2
	v_mov_b32_e32 v115, v2
	v_mov_b32_e32 v116, v2
	v_mov_b32_e32 v117, v2
	v_mov_b32_e32 v118, v2
	v_mov_b32_e32 v119, v2
	v_mov_b32_e32 v120, v2
	v_mov_b32_e32 v121, v2
	v_mov_b32_e32 v74, v2
	v_mov_b32_e32 v75, v2
	v_mov_b32_e32 v76, v2
	v_mov_b32_e32 v77, v2
	v_mov_b32_e32 v78, v2
	v_mov_b32_e32 v79, v2
	v_mov_b32_e32 v80, v2
	v_mov_b32_e32 v81, v2
	v_mov_b32_e32 v90, v2
	v_mov_b32_e32 v91, v2
	v_mov_b32_e32 v92, v2
	v_mov_b32_e32 v93, v2
	v_mov_b32_e32 v94, v2
	v_mov_b32_e32 v95, v2
	v_mov_b32_e32 v96, v2
	v_mov_b32_e32 v97, v2
	v_mov_b32_e32 v106, v2
	v_mov_b32_e32 v107, v2
	v_mov_b32_e32 v108, v2
	v_mov_b32_e32 v109, v2
	v_mov_b32_e32 v110, v2
	v_mov_b32_e32 v111, v2
	v_mov_b32_e32 v112, v2
	v_mov_b32_e32 v113, v2
	v_mov_b32_e32 v122, v2
	v_mov_b32_e32 v123, v2
	v_mov_b32_e32 v124, v2
	v_mov_b32_e32 v125, v2
	v_mov_b32_e32 v126, v2
	v_mov_b32_e32 v127, v2
	v_mov_b32_e32 v128, v2
	v_mov_b32_e32 v129, v2
	s_add_u32 s62, s60, 0xfff80080
	s_addc_u32 s63, s61, -1
	s_add_i32 s86, 0, 0x10000
	s_cmp_eq_u32 s83, 28
	s_cselect_b32 s65, s2, s63
	s_cselect_b32 s64, s3, s62
	s_cselect_b32 s63, s53, s82
	s_cselect_b32 s62, s55, s79
	s_add_i32 s88, 0, 0x14000
	s_branch .LBB0_38

; #define PG8_STAGE(bufoff, gbase, voff) do { _Pragma("unroll") for (int _i = 0; _i < 2; ++_i) \
;         __builtin_amdgcn_global_load_lds((const unsigned*)((const char*)(gbase) + (voff)[_i]), (PG8_LAS unsigned*)(lds + (bufoff) + ldsw + _i * 8192), 16, 0, 0); } while (0)
; #define PG8_LDA(dst, b, h) do { _Pragma("unroll") for (int m = 0; m < 4; ++m) _Pragma("unroll") for (int k = 0; k < 2; ++k) dst[m][k] = *(const PG8_LAS bf16x8*)(lds + PG8_SA(b, h) + aoff + m * 2048 + k * 1024); } while (0)
; #define PG8_LDB(dst, b, h) do { _Pragma("unroll") for (int n = 0; n < 2; ++n) _Pragma("unroll") for (int k = 0; k < 2; ++k) dst[n][k] = *(const PG8_LAS bf16x8*)(lds + PG8_SB(b, h) + boff + n * 2048 + k * 1024); } while (0)
; #define PG8_MMA(ai, bj, At, Bt) do { __builtin_amdgcn_s_setprio(1); _Pragma("unroll") for (int m = 0; m < 4; ++m) _Pragma("unroll") for (int n = 0; n < 2; ++n) _Pragma("unroll") for (int k = 0; k < 2; ++k) \
;         acc[ai][bj][m][n] = __builtin_amdgcn_mfma_f32_16x16x32_bf16(Bt[n][k], At[m][k], acc[ai][bj][m][n], 0, 0, 0); __builtin_amdgcn_s_setprio(0); } while (0)
; #define PG8_WAIT_V(n) asm volatile("s_waitcnt vmcnt(" #n ")" ::: "memory")
; #define PG8_WAIT_L(n) asm volatile("s_waitcnt lgkmcnt(" #n ")" ::: "memory")
; #define PG8_BAR __builtin_amdgcn_s_barrier()
; #define PG8_SCHED __builtin_amdgcn_sched_barrier(0)
; template <class Epi, class Sched, bool ALIGN_EPI = false, bool SP2 = false>
; __device__ __forceinline__ void gemm_phase(PG8_LAS unsigned char* lds, const Gemm g, const Sched& S, const Epi& E) {
;     ...
;             PG8_LDB(B0, 0, 0); PG8_LDB(B1, 0, 1); PG8_SCHED; PG8_LDA(At, 0, 0); PG8_STAGE(PG8_SA(1, 1), a1 + hstep, voffA);
;             PG8_WAIT_V(8); PG8_WAIT_L(0); PG8_BAR; PG8_MMA(0, 0, At, B0); PG8_MMA(0, 1, At, B1); PG8_BAR; PG8_SCHED;
;             PG8_LDA(At, 0, 1); PG8_STAGE(PG8_SB(0, 0), b2, voffB); PG8_STAGE(PG8_SB(0, 1), b2 + hstep, voffB); PG8_STAGE(PG8_SA(0, 0), a2, voffA);
.LBB0_38:
	v_add_u32_e32 v142, s86, v156
	ds_read_b128 v[152:155], v142
	ds_read_b128 v[160:163], v142 offset:1024
	ds_read_b128 v[164:167], v142 offset:2048
	ds_read_b128 v[182:185], v142 offset:3072
	v_add_u32_e32 v142, s88, v156
	ds_read_b128 v[186:189], v142
	ds_read_b128 v[190:193], v142 offset:1024
	ds_read_b128 v[194:197], v142 offset:2048
	ds_read_b128 v[198:201], v142 offset:3072
	v_lshl_add_u64 v[142:143], s[60:61], 0, v[150:151]
	s_add_i32 m0, s69, 0xc000
	ds_read_b128 v[202:205], v158
	ds_read_b128 v[206:209], v158 offset:1024
	ds_read_b128 v[214:217], v158 offset:2048
	ds_read_b128 v[218:221], v158 offset:3072
	ds_read_b128 v[222:225], v158 offset:4096
	ds_read_b128 v[226:229], v158 offset:5120
	ds_read_b128 v[230:233], v158 offset:6144
	ds_read_b128 v[234:237], v158 offset:7168
	global_load_lds_dwordx4 v[142:143], off
	v_lshl_add_u64 v[142:143], s[60:61], 0, v[136:137]
	s_add_i32 m0, s69, 0xe000
	s_nop 0
	global_load_lds_dwordx4 v[142:143], off
	s_waitcnt vmcnt(8)
	s_waitcnt lgkmcnt(0)
	s_setprio 1
	s_barrier
	v_mfma_f32_16x16x32_bf16 v[126:129], v[152:155], v[202:205], v[126:129]
	v_mfma_f32_16x16x32_bf16 v[122:125], v[164:167], v[202:205], v[122:125]
	v_mfma_f32_16x16x32_bf16 v[110:113], v[152:155], v[214:217], v[110:113]
	v_mfma_f32_16x16x32_bf16 v[106:109], v[164:167], v[214:217], v[106:109]
	v_mfma_f32_16x16x32_bf16 v[94:97], v[152:155], v[222:225], v[94:97]
	v_mfma_f32_16x16x32_bf16 v[90:93], v[164:167], v[222:225], v[90:93]
	v_mfma_f32_16x16x32_bf16 v[78:81], v[152:155], v[230:233], v[78:81]
	v_mfma_f32_16x16x32_bf16 v[74:77], v[164:167], v[230:233], v[74:77]
	v_mfma_f32_16x16x32_bf16 v[126:129], v[160:163], v[206:209], v[126:129]
	v_mfma_f32_16x16x32_bf16 v[122:125], v[182:185], v[206:209], v[122:125]
	v_mfma_f32_16x16x32_bf16 v[110:113], v[160:163], v[218:221], v[110:113]
	v_mfma_f32_16x16x32_bf16 v[106:109], v[182:185], v[218:221], v[106:109]
	v_mfma_f32_16x16x32_bf16 v[94:97], v[160:163], v[226:229], v[94:97]
	v_mfma_f32_16x16x32_bf16 v[90:93], v[182:185], v[226:229], v[90:93]
	v_mfma_f32_16x16x32_bf16 v[78:81], v[160:163], v[234:237], v[78:81]
	v_mfma_f32_16x16x32_bf16 v[74:77], v[182:185], v[234:237], v[74:77]
	s_setprio 0
	s_setprio 1
	v_mfma_f32_16x16x32_bf16 v[118:121], v[186:189], v[202:205], v[118:121]
	v_mfma_f32_16x16x32_bf16 v[114:117], v[194:197], v[202:205], v[114:117]
	v_mfma_f32_16x16x32_bf16 v[102:105], v[186:189], v[214:217], v[102:105]
	v_mfma_f32_16x16x32_bf16 v[98:101], v[194:197], v[214:217], v[98:101]
	v_mfma_f32_16x16x32_bf16 v[86:89], v[186:189], v[222:225], v[86:89]
	v_mfma_f32_16x16x32_bf16 v[82:85], v[194:197], v[222:225], v[82:85]
	v_mfma_f32_16x16x32_bf16 v[70:73], v[186:189], v[230:233], v[70:73]
	v_mfma_f32_16x16x32_bf16 v[66:69], v[194:197], v[230:233], v[66:69]
	v_mfma_f32_16x16x32_bf16 v[118:121], v[190:193], v[206:209], v[118:121]
	v_mfma_f32_16x16x32_bf16 v[114:117], v[198:201], v[206:209], v[114:117]
	v_mfma_f32_16x16x32_bf16 v[102:105], v[190:193], v[218:221], v[102:105]
	v_mfma_f32_16x16x32_bf16 v[98:101], v[198:201], v[218:221], v[98:101]
	v_mfma_f32_16x16x32_bf16 v[86:89], v[190:193], v[226:229], v[86:89]
	v_mfma_f32_16x16x32_bf16 v[82:85], v[198:201], v[226:229], v[82:85]
	v_mfma_f32_16x16x32_bf16 v[70:73], v[190:193], v[234:237], v[70:73]
	v_mfma_f32_16x16x32_bf16 v[66:69], v[198:201], v[234:237], v[66:69]
	s_setprio 0
	s_barrier
	s_add_i32 s86, s86, s68
	v_lshl_add_u64 v[142:143], s[62:63], 0, v[0:1]
	s_mov_b32 m0, s86
	ds_read_b128 v[202:205], v158 offset:16384
	ds_read_b128 v[206:209], v158 offset:17408
	ds_read_b128 v[214:217], v158 offset:18432
	ds_read_b128 v[218:221], v158 offset:19456
	ds_read_b128 v[222:225], v158 offset:20480
	ds_read_b128 v[226:229], v158 offset:21504
	ds_read_b128 v[230:233], v158 offset:22528
	ds_read_b128 v[234:237], v158 offset:23552
	global_load_lds_dwordx4 v[142:143], off
	s_add_i32 m0, s86, 0x2000
	s_add_u32 s86, s62, 0x80000
	v_lshl_add_u64 v[144:145], s[62:63], 0, v[130:131]
	s_addc_u32 s87, s63, 0
	s_add_i32 s88, s88, s68
	global_load_lds_dwordx4 v[144:145], off
	v_lshl_add_u64 v[168:169], s[86:87], 0, v[0:1]
	s_mov_b32 m0, s88
	v_lshl_add_u64 v[238:239], s[64:65], 0, v[132:133]
	global_load_lds_dwordx4 v[168:169], off
	v_lshl_add_u64 v[168:169], s[86:87], 0, v[130:131]
	s_add_i32 m0, s88, 0x2000
	s_nop 0
	global_load_lds_dwordx4 v[168:169], off
	v_lshl_add_u64 v[168:169], s[64:65], 0, v[134:135]
	s_mov_b32 m0, s69
	s_nop 0
	global_load_lds_dwordx4 v[168:169], off
	s_mov_b32 m0, s70
	s_nop 0
	global_load_lds_dwordx4 v[238:239], off
	s_waitcnt vmcnt(8)
	s_waitcnt lgkmcnt(0)
	s_setprio 1
	s_barrier
; #define PG8_STAGE(bufoff, gbase, voff) do { _Pragma("unroll") for (int _i = 0; _i < 2; ++_i) \
;         __builtin_amdgcn_global_load_lds((const unsigned*)((const char*)(gbase) + (voff)[_i]), (PG8_LAS unsigned*)(lds + (bufoff) + ldsw + _i * 8192), 16, 0, 0); } while (0)
; #define PG8_LDA(dst, b, h) do { _Pragma("unroll") for (int m = 0; m < 4; ++m) _Pragma("unroll") for (int k = 0; k < 2; ++k) dst[m][k] = *(const PG8_LAS bf16x8*)(lds + PG8_SA(b, h) + aoff + m * 2048 + k * 1024); } while (0)
; #define PG8_LDB(dst, b, h) do { _Pragma("unroll") for (int n = 0; n < 2; ++n) _Pragma("unroll") for (int k = 0; k < 2; ++k) dst[n][k] = *(const PG8_LAS bf16x8*)(lds + PG8_SB(b, h) + boff + n * 2048 + k * 1024); } while (0)
; #define PG8_MMA(ai, bj, At, Bt) do { __builtin_amdgcn_s_setprio(1); _Pragma("unroll") for (int m = 0; m < 4; ++m) _Pragma("unroll") for (int n = 0; n < 2; ++n) _Pragma("unroll") for (int k = 0; k < 2; ++k) \
;         acc[ai][bj][m][n] = __builtin_amdgcn_mfma_f32_16x16x32_bf16(Bt[n][k], At[m][k], acc[ai][bj][m][n], 0, 0, 0); __builtin_amdgcn_s_setprio(0); } while (0)
; #define PG8_WAIT_V(n) asm volatile("s_waitcnt vmcnt(" #n ")" ::: "memory")
; #define PG8_WAIT_L(n) asm volatile("s_waitcnt lgkmcnt(" #n ")" ::: "memory")
; #define PG8_BAR __builtin_amdgcn_s_barrier()
; #define PG8_SCHED __builtin_amdgcn_sched_barrier(0)
; template <class Epi, class Sched, bool ALIGN_EPI = false, bool SP2 = false>
; __device__ __forceinline__ void gemm_phase(PG8_LAS unsigned char* lds, const Gemm g, const Sched& S, const Epi& E) {
;     ...
;             PG8_WAIT_V(8); PG8_WAIT_L(0); PG8_BAR; PG8_MMA(1, 0, At, B0); PG8_MMA(1, 1, At, B1); PG8_BAR; PG8_SCHED;
;             PG8_LDB(B0, 1, 0); PG8_LDB(B1, 1, 1); PG8_SCHED; PG8_LDA(At, 1, 0); PG8_STAGE(PG8_SA(0, 1), a2 + hstep, voffA);
;             PG8_WAIT_V(8); PG8_WAIT_L(0); PG8_BAR; PG8_MMA(0, 0, At, B0); PG8_MMA(0, 1, At, B1); PG8_BAR; PG8_SCHED;
	v_mfma_f32_16x16x32_bf16 v[62:65], v[152:155], v[202:205], v[62:65]
	v_mfma_f32_16x16x32_bf16 v[58:61], v[164:167], v[202:205], v[58:61]
	v_mfma_f32_16x16x32_bf16 v[46:49], v[152:155], v[214:217], v[46:49]
	v_mfma_f32_16x16x32_bf16 v[42:45], v[164:167], v[214:217], v[42:45]
	v_mfma_f32_16x16x32_bf16 v[30:33], v[152:155], v[222:225], v[30:33]
	v_mfma_f32_16x16x32_bf16 v[26:29], v[164:167], v[222:225], v[26:29]
	v_mfma_f32_16x16x32_bf16 v[14:17], v[152:155], v[230:233], v[14:17]
	v_mfma_f32_16x16x32_bf16 v[10:13], v[164:167], v[230:233], v[10:13]
	v_mfma_f32_16x16x32_bf16 v[62:65], v[160:163], v[206:209], v[62:65]
	v_mfma_f32_16x16x32_bf16 v[58:61], v[182:185], v[206:209], v[58:61]
	v_mfma_f32_16x16x32_bf16 v[46:49], v[160:163], v[218:221], v[46:49]
	v_mfma_f32_16x16x32_bf16 v[42:45], v[182:185], v[218:221], v[42:45]
	v_mfma_f32_16x16x32_bf16 v[30:33], v[160:163], v[226:229], v[30:33]
	v_mfma_f32_16x16x32_bf16 v[26:29], v[182:185], v[226:229], v[26:29]
	v_mfma_f32_16x16x32_bf16 v[14:17], v[160:163], v[234:237], v[14:17]
	v_mfma_f32_16x16x32_bf16 v[10:13], v[182:185], v[234:237], v[10:13]
	s_setprio 0
	s_setprio 1
	v_mfma_f32_16x16x32_bf16 v[54:57], v[186:189], v[202:205], v[54:57]
	v_mfma_f32_16x16x32_bf16 v[50:53], v[194:197], v[202:205], v[50:53]
	v_mfma_f32_16x16x32_bf16 v[38:41], v[186:189], v[214:217], v[38:41]
	v_mfma_f32_16x16x32_bf16 v[34:37], v[194:197], v[214:217], v[34:37]
	v_mfma_f32_16x16x32_bf16 v[22:25], v[186:189], v[222:225], v[22:25]
	v_mfma_f32_16x16x32_bf16 v[18:21], v[194:197], v[222:225], v[18:21]
	v_mfma_f32_16x16x32_bf16 v[6:9], v[186:189], v[230:233], v[6:9]
	v_mfma_f32_16x16x32_bf16 v[2:5], v[194:197], v[230:233], v[2:5]
	v_mfma_f32_16x16x32_bf16 v[54:57], v[190:193], v[206:209], v[54:57]
	v_mfma_f32_16x16x32_bf16 v[50:53], v[198:201], v[206:209], v[50:53]
	v_mfma_f32_16x16x32_bf16 v[38:41], v[190:193], v[218:221], v[38:41]
	v_mfma_f32_16x16x32_bf16 v[34:37], v[198:201], v[218:221], v[34:37]
	v_mfma_f32_16x16x32_bf16 v[22:25], v[190:193], v[226:229], v[22:25]
	v_mfma_f32_16x16x32_bf16 v[18:21], v[198:201], v[226:229], v[18:21]
	v_mfma_f32_16x16x32_bf16 v[6:9], v[190:193], v[234:237], v[6:9]
	v_mfma_f32_16x16x32_bf16 v[2:5], v[198:201], v[234:237], v[2:5]
	s_setprio 0
	s_barrier
	s_add_i32 s86, 0, 0x18000
	v_add_u32_e32 v159, s86, v156
	s_add_i32 s87, 0, 0x1c000
	ds_read_b128 v[152:155], v159
	ds_read_b128 v[160:163], v159 offset:1024
	ds_read_b128 v[164:167], v159 offset:2048
	ds_read_b128 v[182:185], v159 offset:3072
	v_add_u32_e32 v159, s87, v156
	ds_read_b128 v[186:189], v159
	ds_read_b128 v[190:193], v159 offset:1024
	ds_read_b128 v[194:197], v159 offset:2048
	ds_read_b128 v[198:201], v159 offset:3072
	s_add_u32 s64, s64, 0x80000
	s_addc_u32 s65, s65, 0
	s_mov_b32 m0, s71
	v_lshl_add_u64 v[240:241], s[64:65], 0, v[134:135]
	ds_read_b128 v[202:205], v158 offset:32768
	ds_read_b128 v[206:209], v158 offset:33792
	ds_read_b128 v[214:217], v158 offset:34816
	ds_read_b128 v[218:221], v158 offset:35840
	ds_read_b128 v[222:225], v158 offset:36864
	ds_read_b128 v[226:229], v158 offset:37888
	ds_read_b128 v[230:233], v158 offset:38912
	ds_read_b128 v[234:237], v158 offset:39936
	global_load_lds_dwordx4 v[240:241], off
	v_lshl_add_u64 v[240:241], s[64:65], 0, v[132:133]
	s_mov_b32 m0, s72
	s_nop 0
	global_load_lds_dwordx4 v[240:241], off
	s_waitcnt vmcnt(8)
	s_waitcnt lgkmcnt(0)
	s_setprio 1
	s_barrier
	v_mfma_f32_16x16x32_bf16 v[126:129], v[152:155], v[202:205], v[126:129]
	v_mfma_f32_16x16x32_bf16 v[122:125], v[164:167], v[202:205], v[122:125]
	v_mfma_f32_16x16x32_bf16 v[110:113], v[152:155], v[214:217], v[110:113]
	v_mfma_f32_16x16x32_bf16 v[106:109], v[164:167], v[214:217], v[106:109]
	v_mfma_f32_16x16x32_bf16 v[94:97], v[152:155], v[222:225], v[94:97]
	v_mfma_f32_16x16x32_bf16 v[90:93], v[164:167], v[222:225], v[90:93]
	v_mfma_f32_16x16x32_bf16 v[78:81], v[152:155], v[230:233], v[78:81]
	v_mfma_f32_16x16x32_bf16 v[74:77], v[164:167], v[230:233], v[74:77]
	v_mfma_f32_16x16x32_bf16 v[126:129], v[160:163], v[206:209], v[126:129]
	v_mfma_f32_16x16x32_bf16 v[122:125], v[182:185], v[206:209], v[122:125]
	v_mfma_f32_16x16x32_bf16 v[110:113], v[160:163], v[218:221], v[110:113]
	v_mfma_f32_16x16x32_bf16 v[106:109], v[182:185], v[218:221], v[106:109]
	v_mfma_f32_16x16x32_bf16 v[94:97], v[160:163], v[226:229], v[94:97]
	v_mfma_f32_16x16x32_bf16 v[90:93], v[182:185], v[226:229], v[90:93]
	v_mfma_f32_16x16x32_bf16 v[78:81], v[160:163], v[234:237], v[78:81]
	v_mfma_f32_16x16x32_bf16 v[74:77], v[182:185], v[234:237], v[74:77]
	s_setprio 0
	s_setprio 1
	v_mfma_f32_16x16x32_bf16 v[118:121], v[186:189], v[202:205], v[118:121]
	v_mfma_f32_16x16x32_bf16 v[114:117], v[194:197], v[202:205], v[114:117]
	v_mfma_f32_16x16x32_bf16 v[102:105], v[186:189], v[214:217], v[102:105]
	v_mfma_f32_16x16x32_bf16 v[98:101], v[194:197], v[214:217], v[98:101]
	v_mfma_f32_16x16x32_bf16 v[86:89], v[186:189], v[222:225], v[86:89]
	v_mfma_f32_16x16x32_bf16 v[82:85], v[194:197], v[222:225], v[82:85]
	v_mfma_f32_16x16x32_bf16 v[70:73], v[186:189], v[230:233], v[70:73]
	v_mfma_f32_16x16x32_bf16 v[66:69], v[194:197], v[230:233], v[66:69]
	v_mfma_f32_16x16x32_bf16 v[118:121], v[190:193], v[206:209], v[118:121]
	v_mfma_f32_16x16x32_bf16 v[114:117], v[198:201], v[206:209], v[114:117]
	v_mfma_f32_16x16x32_bf16 v[102:105], v[190:193], v[218:221], v[102:105]
	v_mfma_f32_16x16x32_bf16 v[98:101], v[198:201], v[218:221], v[98:101]
	v_mfma_f32_16x16x32_bf16 v[86:89], v[190:193], v[226:229], v[86:89]
	v_mfma_f32_16x16x32_bf16 v[82:85], v[198:201], v[226:229], v[82:85]
	v_mfma_f32_16x16x32_bf16 v[70:73], v[190:193], v[234:237], v[70:73]
	v_mfma_f32_16x16x32_bf16 v[66:69], v[198:201], v[234:237], v[66:69]
	s_setprio 0
	s_barrier
; #define PG8_STAGE(bufoff, gbase, voff) do { _Pragma("unroll") for (int _i = 0; _i < 2; ++_i) \
;         __builtin_amdgcn_global_load_lds((const unsigned*)((const char*)(gbase) + (voff)[_i]), (PG8_LAS unsigned*)(lds + (bufoff) + ldsw + _i * 8192), 16, 0, 0); } while (0)
; #define PG8_LDA(dst, b, h) do { _Pragma("unroll") for (int m = 0; m < 4; ++m) _Pragma("unroll") for (int k = 0; k < 2; ++k) dst[m][k] = *(const PG8_LAS bf16x8*)(lds + PG8_SA(b, h) + aoff + m * 2048 + k * 1024); } while (0)
; #define PG8_MMA(ai, bj, At, Bt) do { __builtin_amdgcn_s_setprio(1); _Pragma("unroll") for (int m = 0; m < 4; ++m) _Pragma("unroll") for (int n = 0; n < 2; ++n) _Pragma("unroll") for (int k = 0; k < 2; ++k) \
;         acc[ai][bj][m][n] = __builtin_amdgcn_mfma_f32_16x16x32_bf16(Bt[n][k], At[m][k], acc[ai][bj][m][n], 0, 0, 0); __builtin_amdgcn_s_setprio(0); } while (0)
; #define PG8_WAIT_V(n) asm volatile("s_waitcnt vmcnt(" #n ")" ::: "memory")
; #define PG8_WAIT_L(n) asm volatile("s_waitcnt lgkmcnt(" #n ")" ::: "memory")
; #define PG8_BAR __builtin_amdgcn_s_barrier()
; #define PG8_SCHED __builtin_amdgcn_sched_barrier(0)
; template <class Epi, class Sched, bool ALIGN_EPI = false, bool SP2 = false>
; __device__ __forceinline__ void gemm_phase(PG8_LAS unsigned char* lds, const Gemm g, const Sched& S, const Epi& E) {
;     ...
;         for (int t = 0; t < nt; t += 2) {
;             const bool last = (t == nt - 2);
;             const char* a1 = cA + (size_t)(t + 1) * kstep;
;             const char* a2 = last ? nA : cA + (size_t)(t + 2) * kstep; const char* b2 = last ? nB : cB + (size_t)(t + 2) * kstep;
;             const char* a3 = a2 + kstep; const char* b3 = b2 + kstep;
;     ...
;             PG8_LDA(At, 1, 1); PG8_STAGE(PG8_SB(1, 0), b3, voffB); PG8_STAGE(PG8_SB(1, 1), b3 + hstep, voffB); PG8_STAGE(PG8_SA(1, 0), a3, voffA);
;             PG8_WAIT_V(8); PG8_WAIT_L(0); PG8_BAR; PG8_MMA(1, 0, At, B0); PG8_MMA(1, 1, At, B1); PG8_BAR; PG8_SCHED;
	s_add_i32 s64, s86, s68
	v_lshl_add_u64 v[142:143], v[142:143], 0, s[34:35]
	s_mov_b32 m0, s64
	ds_read_b128 v[202:205], v158 offset:49152
	ds_read_b128 v[206:209], v158 offset:50176
	ds_read_b128 v[214:217], v158 offset:51200
	ds_read_b128 v[218:221], v158 offset:52224
	ds_read_b128 v[222:225], v158 offset:53248
	ds_read_b128 v[226:229], v158 offset:54272
	ds_read_b128 v[230:233], v158 offset:55296
	ds_read_b128 v[234:237], v158 offset:56320
	global_load_lds_dwordx4 v[142:143], off
	s_add_i32 m0, s64, 0x2000
	s_add_u32 s62, s62, 0x80080
	v_lshl_add_u64 v[142:143], v[144:145], 0, s[34:35]
	s_addc_u32 s63, s63, 0
	s_add_i32 s64, s87, s68
	global_load_lds_dwordx4 v[142:143], off
	v_lshl_add_u64 v[142:143], s[62:63], 0, v[0:1]
	s_mov_b32 m0, s64
	s_nop 0
	global_load_lds_dwordx4 v[142:143], off
	v_lshl_add_u64 v[142:143], s[62:63], 0, v[130:131]
	s_add_i32 m0, s64, 0x2000
	s_nop 0
	global_load_lds_dwordx4 v[142:143], off
	v_lshl_add_u64 v[142:143], v[168:169], 0, s[34:35]
	s_mov_b32 m0, s74
	s_nop 0
	global_load_lds_dwordx4 v[142:143], off
	v_lshl_add_u64 v[142:143], v[238:239], 0, s[34:35]
	s_mov_b32 m0, s75
	s_nop 0
	global_load_lds_dwordx4 v[142:143], off
	s_waitcnt vmcnt(8)
	s_waitcnt lgkmcnt(0)
	s_setprio 1
	s_barrier
	v_mfma_f32_16x16x32_bf16 v[62:65], v[152:155], v[202:205], v[62:65]
	v_mfma_f32_16x16x32_bf16 v[58:61], v[164:167], v[202:205], v[58:61]
	v_mfma_f32_16x16x32_bf16 v[46:49], v[152:155], v[214:217], v[46:49]
	v_mfma_f32_16x16x32_bf16 v[42:45], v[164:167], v[214:217], v[42:45]
	v_mfma_f32_16x16x32_bf16 v[30:33], v[152:155], v[222:225], v[30:33]
	v_mfma_f32_16x16x32_bf16 v[26:29], v[164:167], v[222:225], v[26:29]
	v_mfma_f32_16x16x32_bf16 v[14:17], v[152:155], v[230:233], v[14:17]
	v_mfma_f32_16x16x32_bf16 v[10:13], v[164:167], v[230:233], v[10:13]
	v_mfma_f32_16x16x32_bf16 v[62:65], v[160:163], v[206:209], v[62:65]
	v_mfma_f32_16x16x32_bf16 v[58:61], v[182:185], v[206:209], v[58:61]
	v_mfma_f32_16x16x32_bf16 v[46:49], v[160:163], v[218:221], v[46:49]
	v_mfma_f32_16x16x32_bf16 v[42:45], v[182:185], v[218:221], v[42:45]
	v_mfma_f32_16x16x32_bf16 v[30:33], v[160:163], v[226:229], v[30:33]
	v_mfma_f32_16x16x32_bf16 v[26:29], v[182:185], v[226:229], v[26:29]
	v_mfma_f32_16x16x32_bf16 v[14:17], v[160:163], v[234:237], v[14:17]
	v_mfma_f32_16x16x32_bf16 v[10:13], v[182:185], v[234:237], v[10:13]
	s_setprio 0
	s_setprio 1
	v_mfma_f32_16x16x32_bf16 v[54:57], v[186:189], v[202:205], v[54:57]
	v_mfma_f32_16x16x32_bf16 v[50:53], v[194:197], v[202:205], v[50:53]
	v_mfma_f32_16x16x32_bf16 v[38:41], v[186:189], v[214:217], v[38:41]
	v_mfma_f32_16x16x32_bf16 v[34:37], v[194:197], v[214:217], v[34:37]
	v_mfma_f32_16x16x32_bf16 v[22:25], v[186:189], v[222:225], v[22:25]
	v_mfma_f32_16x16x32_bf16 v[18:21], v[194:197], v[222:225], v[18:21]
	v_mfma_f32_16x16x32_bf16 v[6:9], v[186:189], v[230:233], v[6:9]
	v_mfma_f32_16x16x32_bf16 v[2:5], v[194:197], v[230:233], v[2:5]
	v_mfma_f32_16x16x32_bf16 v[54:57], v[190:193], v[206:209], v[54:57]
	v_mfma_f32_16x16x32_bf16 v[50:53], v[198:201], v[206:209], v[50:53]
	v_mfma_f32_16x16x32_bf16 v[38:41], v[190:193], v[218:221], v[38:41]
	v_mfma_f32_16x16x32_bf16 v[34:37], v[198:201], v[218:221], v[34:37]
	v_mfma_f32_16x16x32_bf16 v[22:25], v[190:193], v[226:229], v[22:25]
	v_mfma_f32_16x16x32_bf16 v[18:21], v[198:201], v[226:229], v[18:21]
	v_mfma_f32_16x16x32_bf16 v[6:9], v[190:193], v[234:237], v[6:9]
	v_mfma_f32_16x16x32_bf16 v[2:5], v[198:201], v[234:237], v[2:5]
	s_setprio 0
	s_add_i32 s83, s83, 2
	s_add_u32 s79, s79, 0x100
	s_addc_u32 s82, s82, 0
	s_add_u32 s60, s60, 0x100
	s_addc_u32 s61, s61, 0
	s_cmp_gt_u32 s83, 29
	s_cbranch_scc1 .Lg3_exit_bar
	s_add_u32 s62, s60, 0xfff80080
	s_addc_u32 s63, s61, -1
	s_add_i32 s86, 0, 0x10000
	s_cmp_eq_u32 s83, 28
	s_cselect_b32 s65, s2, s63
	s_cselect_b32 s64, s3, s62
	s_cselect_b32 s63, s53, s82
	s_cselect_b32 s62, s55, s79
	s_add_i32 s88, 0, 0x14000
	s_branch .Lg3_head_bar
.Lg3_exit_bar:
	s_barrier
	s_and_b64 vcc, exec, s[50:51]
	s_cbranch_vccz .LBB0_41
	s_barrier

; template <class Epi, class Sched, bool ALIGN_EPI = false, bool SP2 = false>
; __device__ __forceinline__ void gemm_phase(PG8_LAS unsigned char* lds, const Gemm g, const Sched& S, const Epi& E) {
;     ...
;     f32x4 acc[2][2][4][2];
; #pragma unroll
;     for (int a = 0; a < 2; ++a)
; #pragma unroll
;         for (int b = 0; b < 2; ++b)
; #pragma unroll
;             for (int m = 0; m < 4; ++m)
; #pragma unroll
;                 for (int n = 0; n < 2; ++n) acc[a][b][m][n] = (f32x4){0.f, 0.f, 0.f, 0.f};
;     bf16x8 At[4][2], B0[2][2], B1[2][2];
;     const char* cA = (const char*)g.A + (size_t)cur.pm * tstep; const char* cB = (const char*)g.Bt + (size_t)cur.pn * tstep;
;     ...
;         const char* nA = has_next ? (const char*)g.A + (size_t)nxt.pm * tstep : cA; const char* nB = has_next ? (const char*)g.Bt + (size_t)nxt.pn * tstep : cB;
;         for (int t = 0; t < nt; t += 2) {
;             const bool last = (t == nt - 2);
;             const char* a1 = cA + (size_t)(t + 1) * kstep;
;             const char* a2 = last ? nA : cA + (size_t)(t + 2) * kstep; const char* b2 = last ? nB : cB + (size_t)(t + 2) * kstep;
;             const char* a3 = a2 + kstep; const char* b3 = b2 + kstep;
.LBB0_417:
	s_ashr_i32 s51, s50, 31
	s_lshl_b64 s[2:3], s[50:51], 20
	s_add_u32 s52, s46, s2
	s_addc_u32 s53, s47, s3
	s_and_b64 s[2:3], s[38:39], exec
	s_cselect_b32 s2, s53, s57
	s_cselect_b32 s3, s52, s56
	s_ashr_i32 s49, s48, 31
	s_lshl_b64 s[54:55], s[48:49], 20
	s_add_u32 s54, s60, s54
	s_addc_u32 s55, s61, s55
	s_and_b64 s[58:59], s[38:39], exec
	s_cselect_b32 s49, s55, s41
	s_cselect_b32 s51, s54, s40
	s_add_u32 s72, s40, 0x100
	s_addc_u32 s73, s41, 0
	s_add_u32 s40, s56, 0x80080
	v_mov_b32_e32 v2, 0
	s_addc_u32 s41, s57, 0
	s_mov_b32 s74, -2
	v_mov_b32_e32 v3, v2
	v_mov_b32_e32 v4, v2
	v_mov_b32_e32 v5, v2
	v_mov_b32_e32 v6, v2
	v_mov_b32_e32 v7, v2
	v_mov_b32_e32 v8, v2
	v_mov_b32_e32 v9, v2
	v_mov_b32_e32 v18, v2
	v_mov_b32_e32 v19, v2
	v_mov_b32_e32 v20, v2
	v_mov_b32_e32 v21, v2
	v_mov_b32_e32 v22, v2
	v_mov_b32_e32 v23, v2
	v_mov_b32_e32 v24, v2
	v_mov_b32_e32 v25, v2
	v_mov_b32_e32 v34, v2
	v_mov_b32_e32 v35, v2
	v_mov_b32_e32 v36, v2
	v_mov_b32_e32 v37, v2
	v_mov_b32_e32 v38, v2
	v_mov_b32_e32 v39, v2
	v_mov_b32_e32 v40, v2
	v_mov_b32_e32 v41, v2
	v_mov_b32_e32 v50, v2
	v_mov_b32_e32 v51, v2
	v_mov_b32_e32 v52, v2
	v_mov_b32_e32 v53, v2
	v_mov_b32_e32 v54, v2
	v_mov_b32_e32 v55, v2
	v_mov_b32_e32 v56, v2
	v_mov_b32_e32 v57, v2
	v_mov_b32_e32 v10, v2
	v_mov_b32_e32 v11, v2
	v_mov_b32_e32 v12, v2
	v_mov_b32_e32 v13, v2
	v_mov_b32_e32 v14, v2
	v_mov_b32_e32 v15, v2
	v_mov_b32_e32 v16, v2
	v_mov_b32_e32 v17, v2
	v_mov_b32_e32 v26, v2
	v_mov_b32_e32 v27, v2
	v_mov_b32_e32 v28, v2
	v_mov_b32_e32 v29, v2
	v_mov_b32_e32 v30, v2
	v_mov_b32_e32 v31, v2
	v_mov_b32_e32 v32, v2
	v_mov_b32_e32 v33, v2
	v_mov_b32_e32 v42, v2
	v_mov_b32_e32 v43, v2
	v_mov_b32_e32 v44, v2
	v_mov_b32_e32 v45, v2
	v_mov_b32_e32 v46, v2
	v_mov_b32_e32 v47, v2
	v_mov_b32_e32 v48, v2
	v_mov_b32_e32 v49, v2
	v_mov_b32_e32 v58, v2
	v_mov_b32_e32 v59, v2
	v_mov_b32_e32 v60, v2
	v_mov_b32_e32 v61, v2
	v_mov_b32_e32 v62, v2
	v_mov_b32_e32 v63, v2
	v_mov_b32_e32 v64, v2
	v_mov_b32_e32 v65, v2
	v_mov_b32_e32 v66, v2
	v_mov_b32_e32 v67, v2
	v_mov_b32_e32 v68, v2
	v_mov_b32_e32 v69, v2
	v_mov_b32_e32 v70, v2
	v_mov_b32_e32 v71, v2
	v_mov_b32_e32 v72, v2
	v_mov_b32_e32 v73, v2
	v_mov_b32_e32 v82, v2
	v_mov_b32_e32 v83, v2
	v_mov_b32_e32 v84, v2
	v_mov_b32_e32 v85, v2
	v_mov_b32_e32 v86, v2
	v_mov_b32_e32 v87, v2
	v_mov_b32_e32 v88, v2
	v_mov_b32_e32 v89, v2
	v_mov_b32_e32 v98, v2
	v_mov_b32_e32 v99, v2
	v_mov_b32_e32 v100, v2
	v_mov_b32_e32 v101, v2
	v_mov_b32_e32 v102, v2
	v_mov_b32_e32 v103, v2
	v_mov_b32_e32 v104, v2
	v_mov_b32_e32 v105, v2
	v_mov_b32_e32 v114, v2
	v_mov_b32_e32 v115, v2
	v_mov_b32_e32 v116, v2
	v_mov_b32_e32 v117, v2
	v_mov_b32_e32 v118, v2
	v_mov_b32_e32 v119, v2
	v_mov_b32_e32 v120, v2
	v_mov_b32_e32 v121, v2
	v_mov_b32_e32 v74, v2
	v_mov_b32_e32 v75, v2
	v_mov_b32_e32 v76, v2
	v_mov_b32_e32 v77, v2
	v_mov_b32_e32 v78, v2
	v_mov_b32_e32 v79, v2
	v_mov_b32_e32 v80, v2
	v_mov_b32_e32 v81, v2
	v_mov_b32_e32 v90, v2
	v_mov_b32_e32 v91, v2
	v_mov_b32_e32 v92, v2
	v_mov_b32_e32 v93, v2
	v_mov_b32_e32 v94, v2
	v_mov_b32_e32 v95, v2
	v_mov_b32_e32 v96, v2
	v_mov_b32_e32 v97, v2
	v_mov_b32_e32 v106, v2
	v_mov_b32_e32 v107, v2
	v_mov_b32_e32 v108, v2
	v_mov_b32_e32 v109, v2
	v_mov_b32_e32 v110, v2
	v_mov_b32_e32 v111, v2
	v_mov_b32_e32 v112, v2
	v_mov_b32_e32 v113, v2
	v_mov_b32_e32 v122, v2
	v_mov_b32_e32 v123, v2
	v_mov_b32_e32 v124, v2
	v_mov_b32_e32 v125, v2
	v_mov_b32_e32 v126, v2
	v_mov_b32_e32 v127, v2
	v_mov_b32_e32 v128, v2
	v_mov_b32_e32 v129, v2
	s_add_u32 s56, s40, 0xfff80080
	s_addc_u32 s57, s41, -1
	s_add_i32 s75, 0, 0x10000
	s_cmp_eq_u32 s74, 28
	s_cselect_b32 s59, s2, s57
	s_cselect_b32 s58, s3, s56
	s_cselect_b32 s57, s49, s73
	s_cselect_b32 s56, s51, s72
	s_add_i32 s78, 0, 0x14000
	s_branch .LBB0_418

; #define PG8_STAGE(bufoff, gbase, voff) do { _Pragma("unroll") for (int _i = 0; _i < 2; ++_i) \
;         __builtin_amdgcn_global_load_lds((const unsigned*)((const char*)(gbase) + (voff)[_i]), (PG8_LAS unsigned*)(lds + (bufoff) + ldsw + _i * 8192), 16, 0, 0); } while (0)
; #define PG8_LDA(dst, b, h) do { _Pragma("unroll") for (int m = 0; m < 4; ++m) _Pragma("unroll") for (int k = 0; k < 2; ++k) dst[m][k] = *(const PG8_LAS bf16x8*)(lds + PG8_SA(b, h) + aoff + m * 2048 + k * 1024); } while (0)
; #define PG8_LDB(dst, b, h) do { _Pragma("unroll") for (int n = 0; n < 2; ++n) _Pragma("unroll") for (int k = 0; k < 2; ++k) dst[n][k] = *(const PG8_LAS bf16x8*)(lds + PG8_SB(b, h) + boff + n * 2048 + k * 1024); } while (0)
; #define PG8_MMA(ai, bj, At, Bt) do { __builtin_amdgcn_s_setprio(1); _Pragma("unroll") for (int m = 0; m < 4; ++m) _Pragma("unroll") for (int n = 0; n < 2; ++n) _Pragma("unroll") for (int k = 0; k < 2; ++k) \
;         acc[ai][bj][m][n] = __builtin_amdgcn_mfma_f32_16x16x32_bf16(Bt[n][k], At[m][k], acc[ai][bj][m][n], 0, 0, 0); __builtin_amdgcn_s_setprio(0); } while (0)
; #define PG8_WAIT_V(n) asm volatile("s_waitcnt vmcnt(" #n ")" ::: "memory")
; #define PG8_WAIT_L(n) asm volatile("s_waitcnt lgkmcnt(" #n ")" ::: "memory")
; #define PG8_BAR __builtin_amdgcn_s_barrier()
; #define PG8_SCHED __builtin_amdgcn_sched_barrier(0)
; template <class Epi, class Sched, bool ALIGN_EPI = false, bool SP2 = false>
; __device__ __forceinline__ void gemm_phase(PG8_LAS unsigned char* lds, const Gemm g, const Sched& S, const Epi& E) {
;     ...
;             PG8_LDB(B0, 0, 0); PG8_LDB(B1, 0, 1); PG8_SCHED; PG8_LDA(At, 0, 0); PG8_STAGE(PG8_SA(1, 1), a1 + hstep, voffA);
;             PG8_WAIT_V(8); PG8_WAIT_L(0); PG8_BAR; PG8_MMA(0, 0, At, B0); PG8_MMA(0, 1, At, B1); PG8_BAR; PG8_SCHED;
;             PG8_LDA(At, 0, 1); PG8_STAGE(PG8_SB(0, 0), b2, voffB); PG8_STAGE(PG8_SB(0, 1), b2 + hstep, voffB); PG8_STAGE(PG8_SA(0, 0), a2, voffA);
.LBB0_418:
	v_add_u32_e32 v142, s75, v156
	ds_read_b128 v[152:155], v142
	ds_read_b128 v[160:163], v142 offset:1024
	ds_read_b128 v[164:167], v142 offset:2048
	ds_read_b128 v[182:185], v142 offset:3072
	v_add_u32_e32 v142, s78, v156
	ds_read_b128 v[186:189], v142
	ds_read_b128 v[190:193], v142 offset:1024
	ds_read_b128 v[194:197], v142 offset:2048
	ds_read_b128 v[198:201], v142 offset:3072
	v_lshl_add_u64 v[168:169], s[40:41], 0, v[150:151]
	s_add_i32 m0, s63, 0xc000
	ds_read_b128 v[202:205], v158
	ds_read_b128 v[206:209], v158 offset:1024
	ds_read_b128 v[214:217], v158 offset:2048
	ds_read_b128 v[218:221], v158 offset:3072
	ds_read_b128 v[222:225], v158 offset:4096
	ds_read_b128 v[226:229], v158 offset:5120
	ds_read_b128 v[230:233], v158 offset:6144
	ds_read_b128 v[234:237], v158 offset:7168
	global_load_lds_dwordx4 v[168:169], off
	v_lshl_add_u64 v[168:169], s[40:41], 0, v[136:137]
	s_add_i32 m0, s63, 0xe000
	s_nop 0
	global_load_lds_dwordx4 v[168:169], off
	s_waitcnt vmcnt(8)
	s_waitcnt lgkmcnt(0)
	s_setprio 1
	s_barrier
	v_mfma_f32_16x16x32_bf16 v[126:129], v[152:155], v[202:205], v[126:129]
	v_mfma_f32_16x16x32_bf16 v[122:125], v[164:167], v[202:205], v[122:125]
	v_mfma_f32_16x16x32_bf16 v[110:113], v[152:155], v[214:217], v[110:113]
	v_mfma_f32_16x16x32_bf16 v[106:109], v[164:167], v[214:217], v[106:109]
	v_mfma_f32_16x16x32_bf16 v[94:97], v[152:155], v[222:225], v[94:97]
	v_mfma_f32_16x16x32_bf16 v[90:93], v[164:167], v[222:225], v[90:93]
	v_mfma_f32_16x16x32_bf16 v[78:81], v[152:155], v[230:233], v[78:81]
	v_mfma_f32_16x16x32_bf16 v[74:77], v[164:167], v[230:233], v[74:77]
	v_mfma_f32_16x16x32_bf16 v[126:129], v[160:163], v[206:209], v[126:129]
	v_mfma_f32_16x16x32_bf16 v[122:125], v[182:185], v[206:209], v[122:125]
	v_mfma_f32_16x16x32_bf16 v[110:113], v[160:163], v[218:221], v[110:113]
	v_mfma_f32_16x16x32_bf16 v[106:109], v[182:185], v[218:221], v[106:109]
	v_mfma_f32_16x16x32_bf16 v[94:97], v[160:163], v[226:229], v[94:97]
	v_mfma_f32_16x16x32_bf16 v[90:93], v[182:185], v[226:229], v[90:93]
	v_mfma_f32_16x16x32_bf16 v[78:81], v[160:163], v[234:237], v[78:81]
	v_mfma_f32_16x16x32_bf16 v[74:77], v[182:185], v[234:237], v[74:77]
	s_setprio 0
	s_setprio 1
	v_mfma_f32_16x16x32_bf16 v[118:121], v[186:189], v[202:205], v[118:121]
	v_mfma_f32_16x16x32_bf16 v[114:117], v[194:197], v[202:205], v[114:117]
	v_mfma_f32_16x16x32_bf16 v[102:105], v[186:189], v[214:217], v[102:105]
	v_mfma_f32_16x16x32_bf16 v[98:101], v[194:197], v[214:217], v[98:101]
	v_mfma_f32_16x16x32_bf16 v[86:89], v[186:189], v[222:225], v[86:89]
	v_mfma_f32_16x16x32_bf16 v[82:85], v[194:197], v[222:225], v[82:85]
	v_mfma_f32_16x16x32_bf16 v[70:73], v[186:189], v[230:233], v[70:73]
	v_mfma_f32_16x16x32_bf16 v[66:69], v[194:197], v[230:233], v[66:69]
	v_mfma_f32_16x16x32_bf16 v[118:121], v[190:193], v[206:209], v[118:121]
	v_mfma_f32_16x16x32_bf16 v[114:117], v[198:201], v[206:209], v[114:117]
	v_mfma_f32_16x16x32_bf16 v[102:105], v[190:193], v[218:221], v[102:105]
	v_mfma_f32_16x16x32_bf16 v[98:101], v[198:201], v[218:221], v[98:101]
	v_mfma_f32_16x16x32_bf16 v[86:89], v[190:193], v[226:229], v[86:89]
	v_mfma_f32_16x16x32_bf16 v[82:85], v[198:201], v[226:229], v[82:85]
	v_mfma_f32_16x16x32_bf16 v[70:73], v[190:193], v[234:237], v[70:73]
	v_mfma_f32_16x16x32_bf16 v[66:69], v[198:201], v[234:237], v[66:69]
	s_setprio 0
	s_barrier
	s_add_i32 s75, s75, s62
	v_lshl_add_u64 v[168:169], s[56:57], 0, v[0:1]
	s_mov_b32 m0, s75
	ds_read_b128 v[202:205], v158 offset:16384
	ds_read_b128 v[206:209], v158 offset:17408
	ds_read_b128 v[214:217], v158 offset:18432
	ds_read_b128 v[218:221], v158 offset:19456
	ds_read_b128 v[222:225], v158 offset:20480
	ds_read_b128 v[226:229], v158 offset:21504
	ds_read_b128 v[230:233], v158 offset:22528
	ds_read_b128 v[234:237], v158 offset:23552
	global_load_lds_dwordx4 v[168:169], off
	s_add_i32 m0, s75, 0x2000
	s_add_u32 s76, s56, 0x80000
	v_lshl_add_u64 v[238:239], s[56:57], 0, v[130:131]
	s_addc_u32 s77, s57, 0
	s_add_i32 s75, s78, s62
	global_load_lds_dwordx4 v[238:239], off
	v_lshl_add_u64 v[240:241], s[76:77], 0, v[0:1]
	s_mov_b32 m0, s75
	v_lshl_add_u64 v[242:243], s[58:59], 0, v[132:133]
	global_load_lds_dwordx4 v[240:241], off
	v_lshl_add_u64 v[240:241], s[76:77], 0, v[130:131]
	s_add_i32 m0, s75, 0x2000
	s_nop 0
	global_load_lds_dwordx4 v[240:241], off
	v_lshl_add_u64 v[240:241], s[58:59], 0, v[134:135]
	s_mov_b32 m0, s63
	s_nop 0
	global_load_lds_dwordx4 v[240:241], off
	s_mov_b32 m0, s64
	s_nop 0
	global_load_lds_dwordx4 v[242:243], off
	s_waitcnt vmcnt(8)
	s_waitcnt lgkmcnt(0)
	s_setprio 1
	s_barrier
; #define PG8_STAGE(bufoff, gbase, voff) do { _Pragma("unroll") for (int _i = 0; _i < 2; ++_i) \
;         __builtin_amdgcn_global_load_lds((const unsigned*)((const char*)(gbase) + (voff)[_i]), (PG8_LAS unsigned*)(lds + (bufoff) + ldsw + _i * 8192), 16, 0, 0); } while (0)
; #define PG8_LDA(dst, b, h) do { _Pragma("unroll") for (int m = 0; m < 4; ++m) _Pragma("unroll") for (int k = 0; k < 2; ++k) dst[m][k] = *(const PG8_LAS bf16x8*)(lds + PG8_SA(b, h) + aoff + m * 2048 + k * 1024); } while (0)
; #define PG8_LDB(dst, b, h) do { _Pragma("unroll") for (int n = 0; n < 2; ++n) _Pragma("unroll") for (int k = 0; k < 2; ++k) dst[n][k] = *(const PG8_LAS bf16x8*)(lds + PG8_SB(b, h) + boff + n * 2048 + k * 1024); } while (0)
; #define PG8_MMA(ai, bj, At, Bt) do { __builtin_amdgcn_s_setprio(1); _Pragma("unroll") for (int m = 0; m < 4; ++m) _Pragma("unroll") for (int n = 0; n < 2; ++n) _Pragma("unroll") for (int k = 0; k < 2; ++k) \
;         acc[ai][bj][m][n] = __builtin_amdgcn_mfma_f32_16x16x32_bf16(Bt[n][k], At[m][k], acc[ai][bj][m][n], 0, 0, 0); __builtin_amdgcn_s_setprio(0); } while (0)
; #define PG8_WAIT_V(n) asm volatile("s_waitcnt vmcnt(" #n ")" ::: "memory")
; #define PG8_WAIT_L(n) asm volatile("s_waitcnt lgkmcnt(" #n ")" ::: "memory")
; #define PG8_BAR __builtin_amdgcn_s_barrier()
; #define PG8_SCHED __builtin_amdgcn_sched_barrier(0)
; template <class Epi, class Sched, bool ALIGN_EPI = false, bool SP2 = false>
; __device__ __forceinline__ void gemm_phase(PG8_LAS unsigned char* lds, const Gemm g, const Sched& S, const Epi& E) {
;     ...
;             PG8_WAIT_V(8); PG8_WAIT_L(0); PG8_BAR; PG8_MMA(1, 0, At, B0); PG8_MMA(1, 1, At, B1); PG8_BAR; PG8_SCHED;
;             PG8_LDB(B0, 1, 0); PG8_LDB(B1, 1, 1); PG8_SCHED; PG8_LDA(At, 1, 0); PG8_STAGE(PG8_SA(0, 1), a2 + hstep, voffA);
;             PG8_WAIT_V(8); PG8_WAIT_L(0); PG8_BAR; PG8_MMA(0, 0, At, B0); PG8_MMA(0, 1, At, B1); PG8_BAR; PG8_SCHED;
	v_mfma_f32_16x16x32_bf16 v[62:65], v[152:155], v[202:205], v[62:65]
	v_mfma_f32_16x16x32_bf16 v[58:61], v[164:167], v[202:205], v[58:61]
	v_mfma_f32_16x16x32_bf16 v[46:49], v[152:155], v[214:217], v[46:49]
	v_mfma_f32_16x16x32_bf16 v[42:45], v[164:167], v[214:217], v[42:45]
	v_mfma_f32_16x16x32_bf16 v[30:33], v[152:155], v[222:225], v[30:33]
	v_mfma_f32_16x16x32_bf16 v[26:29], v[164:167], v[222:225], v[26:29]
	v_mfma_f32_16x16x32_bf16 v[14:17], v[152:155], v[230:233], v[14:17]
	v_mfma_f32_16x16x32_bf16 v[10:13], v[164:167], v[230:233], v[10:13]
	v_mfma_f32_16x16x32_bf16 v[62:65], v[160:163], v[206:209], v[62:65]
	v_mfma_f32_16x16x32_bf16 v[58:61], v[182:185], v[206:209], v[58:61]
	v_mfma_f32_16x16x32_bf16 v[46:49], v[160:163], v[218:221], v[46:49]
	v_mfma_f32_16x16x32_bf16 v[42:45], v[182:185], v[218:221], v[42:45]
	v_mfma_f32_16x16x32_bf16 v[30:33], v[160:163], v[226:229], v[30:33]
	v_mfma_f32_16x16x32_bf16 v[26:29], v[182:185], v[226:229], v[26:29]
	v_mfma_f32_16x16x32_bf16 v[14:17], v[160:163], v[234:237], v[14:17]
	v_mfma_f32_16x16x32_bf16 v[10:13], v[182:185], v[234:237], v[10:13]
	s_setprio 0
	s_setprio 1
	v_mfma_f32_16x16x32_bf16 v[54:57], v[186:189], v[202:205], v[54:57]
	v_mfma_f32_16x16x32_bf16 v[50:53], v[194:197], v[202:205], v[50:53]
	v_mfma_f32_16x16x32_bf16 v[38:41], v[186:189], v[214:217], v[38:41]
	v_mfma_f32_16x16x32_bf16 v[34:37], v[194:197], v[214:217], v[34:37]
	v_mfma_f32_16x16x32_bf16 v[22:25], v[186:189], v[222:225], v[22:25]
	v_mfma_f32_16x16x32_bf16 v[18:21], v[194:197], v[222:225], v[18:21]
	v_mfma_f32_16x16x32_bf16 v[6:9], v[186:189], v[230:233], v[6:9]
	v_mfma_f32_16x16x32_bf16 v[2:5], v[194:197], v[230:233], v[2:5]
	v_mfma_f32_16x16x32_bf16 v[54:57], v[190:193], v[206:209], v[54:57]
	v_mfma_f32_16x16x32_bf16 v[50:53], v[198:201], v[206:209], v[50:53]
	v_mfma_f32_16x16x32_bf16 v[38:41], v[190:193], v[218:221], v[38:41]
	v_mfma_f32_16x16x32_bf16 v[34:37], v[198:201], v[218:221], v[34:37]
	v_mfma_f32_16x16x32_bf16 v[22:25], v[190:193], v[226:229], v[22:25]
	v_mfma_f32_16x16x32_bf16 v[18:21], v[198:201], v[226:229], v[18:21]
	v_mfma_f32_16x16x32_bf16 v[6:9], v[190:193], v[234:237], v[6:9]
	v_mfma_f32_16x16x32_bf16 v[2:5], v[198:201], v[234:237], v[2:5]
	s_setprio 0
	s_barrier
	s_add_i32 s75, 0, 0x18000
	v_add_u32_e32 v142, s75, v156
	s_add_i32 s76, 0, 0x1c000
	ds_read_b128 v[152:155], v142
	ds_read_b128 v[160:163], v142 offset:1024
	ds_read_b128 v[164:167], v142 offset:2048
	ds_read_b128 v[182:185], v142 offset:3072
	v_add_u32_e32 v142, s76, v156
	ds_read_b128 v[186:189], v142
	ds_read_b128 v[190:193], v142 offset:1024
	ds_read_b128 v[194:197], v142 offset:2048
	ds_read_b128 v[198:201], v142 offset:3072
	s_add_u32 s58, s58, 0x80000
	s_addc_u32 s59, s59, 0
	s_mov_b32 m0, s65
	v_lshl_add_u64 v[244:245], s[58:59], 0, v[134:135]
	ds_read_b128 v[202:205], v158 offset:32768
	ds_read_b128 v[206:209], v158 offset:33792
	ds_read_b128 v[214:217], v158 offset:34816
	ds_read_b128 v[218:221], v158 offset:35840
	ds_read_b128 v[222:225], v158 offset:36864
	ds_read_b128 v[226:229], v158 offset:37888
	ds_read_b128 v[230:233], v158 offset:38912
	ds_read_b128 v[234:237], v158 offset:39936
	global_load_lds_dwordx4 v[244:245], off
	v_lshl_add_u64 v[244:245], s[58:59], 0, v[132:133]
	s_mov_b32 m0, s66
	s_nop 0
	global_load_lds_dwordx4 v[244:245], off
	s_waitcnt vmcnt(8)
	s_waitcnt lgkmcnt(0)
	s_setprio 1
	s_barrier
	v_mfma_f32_16x16x32_bf16 v[126:129], v[152:155], v[202:205], v[126:129]
	v_mfma_f32_16x16x32_bf16 v[122:125], v[164:167], v[202:205], v[122:125]
	v_mfma_f32_16x16x32_bf16 v[110:113], v[152:155], v[214:217], v[110:113]
	v_mfma_f32_16x16x32_bf16 v[106:109], v[164:167], v[214:217], v[106:109]
	v_mfma_f32_16x16x32_bf16 v[94:97], v[152:155], v[222:225], v[94:97]
	v_mfma_f32_16x16x32_bf16 v[90:93], v[164:167], v[222:225], v[90:93]
	v_mfma_f32_16x16x32_bf16 v[78:81], v[152:155], v[230:233], v[78:81]
	v_mfma_f32_16x16x32_bf16 v[74:77], v[164:167], v[230:233], v[74:77]
	v_mfma_f32_16x16x32_bf16 v[126:129], v[160:163], v[206:209], v[126:129]
	v_mfma_f32_16x16x32_bf16 v[122:125], v[182:185], v[206:209], v[122:125]
	v_mfma_f32_16x16x32_bf16 v[110:113], v[160:163], v[218:221], v[110:113]
	v_mfma_f32_16x16x32_bf16 v[106:109], v[182:185], v[218:221], v[106:109]
	v_mfma_f32_16x16x32_bf16 v[94:97], v[160:163], v[226:229], v[94:97]
	v_mfma_f32_16x16x32_bf16 v[90:93], v[182:185], v[226:229], v[90:93]
	v_mfma_f32_16x16x32_bf16 v[78:81], v[160:163], v[234:237], v[78:81]
	v_mfma_f32_16x16x32_bf16 v[74:77], v[182:185], v[234:237], v[74:77]
	s_setprio 0
	s_setprio 1
	v_mfma_f32_16x16x32_bf16 v[118:121], v[186:189], v[202:205], v[118:121]
	v_mfma_f32_16x16x32_bf16 v[114:117], v[194:197], v[202:205], v[114:117]
	v_mfma_f32_16x16x32_bf16 v[102:105], v[186:189], v[214:217], v[102:105]
	v_mfma_f32_16x16x32_bf16 v[98:101], v[194:197], v[214:217], v[98:101]
	v_mfma_f32_16x16x32_bf16 v[86:89], v[186:189], v[222:225], v[86:89]
	v_mfma_f32_16x16x32_bf16 v[82:85], v[194:197], v[222:225], v[82:85]
	v_mfma_f32_16x16x32_bf16 v[70:73], v[186:189], v[230:233], v[70:73]
	v_mfma_f32_16x16x32_bf16 v[66:69], v[194:197], v[230:233], v[66:69]
	v_mfma_f32_16x16x32_bf16 v[118:121], v[190:193], v[206:209], v[118:121]
	v_mfma_f32_16x16x32_bf16 v[114:117], v[198:201], v[206:209], v[114:117]
	v_mfma_f32_16x16x32_bf16 v[102:105], v[190:193], v[218:221], v[102:105]
	v_mfma_f32_16x16x32_bf16 v[98:101], v[198:201], v[218:221], v[98:101]
	v_mfma_f32_16x16x32_bf16 v[86:89], v[190:193], v[226:229], v[86:89]
	v_mfma_f32_16x16x32_bf16 v[82:85], v[198:201], v[226:229], v[82:85]
	v_mfma_f32_16x16x32_bf16 v[70:73], v[190:193], v[234:237], v[70:73]
	v_mfma_f32_16x16x32_bf16 v[66:69], v[198:201], v[234:237], v[66:69]
	s_setprio 0
	s_barrier
; #define PG8_STAGE(bufoff, gbase, voff) do { _Pragma("unroll") for (int _i = 0; _i < 2; ++_i) \
;         __builtin_amdgcn_global_load_lds((const unsigned*)((const char*)(gbase) + (voff)[_i]), (PG8_LAS unsigned*)(lds + (bufoff) + ldsw + _i * 8192), 16, 0, 0); } while (0)
; #define PG8_LDA(dst, b, h) do { _Pragma("unroll") for (int m = 0; m < 4; ++m) _Pragma("unroll") for (int k = 0; k < 2; ++k) dst[m][k] = *(const PG8_LAS bf16x8*)(lds + PG8_SA(b, h) + aoff + m * 2048 + k * 1024); } while (0)
; #define PG8_MMA(ai, bj, At, Bt) do { __builtin_amdgcn_s_setprio(1); _Pragma("unroll") for (int m = 0; m < 4; ++m) _Pragma("unroll") for (int n = 0; n < 2; ++n) _Pragma("unroll") for (int k = 0; k < 2; ++k) \
;         acc[ai][bj][m][n] = __builtin_amdgcn_mfma_f32_16x16x32_bf16(Bt[n][k], At[m][k], acc[ai][bj][m][n], 0, 0, 0); __builtin_amdgcn_s_setprio(0); } while (0)
; #define PG8_WAIT_V(n) asm volatile("s_waitcnt vmcnt(" #n ")" ::: "memory")
; #define PG8_WAIT_L(n) asm volatile("s_waitcnt lgkmcnt(" #n ")" ::: "memory")
; #define PG8_BAR __builtin_amdgcn_s_barrier()
; #define PG8_SCHED __builtin_amdgcn_sched_barrier(0)
; template <class Epi, class Sched, bool ALIGN_EPI = false, bool SP2 = false>
; __device__ __forceinline__ void gemm_phase(PG8_LAS unsigned char* lds, const Gemm g, const Sched& S, const Epi& E) {
;     ...
;         for (int t = 0; t < nt; t += 2) {
;             const bool last = (t == nt - 2);
;             const char* a1 = cA + (size_t)(t + 1) * kstep;
;             const char* a2 = last ? nA : cA + (size_t)(t + 2) * kstep; const char* b2 = last ? nB : cB + (size_t)(t + 2) * kstep;
;             const char* a3 = a2 + kstep; const char* b3 = b2 + kstep;
;     ...
;             PG8_LDA(At, 1, 1); PG8_STAGE(PG8_SB(1, 0), b3, voffB); PG8_STAGE(PG8_SB(1, 1), b3 + hstep, voffB); PG8_STAGE(PG8_SA(1, 0), a3, voffA);
;             PG8_WAIT_V(8); PG8_WAIT_L(0); PG8_BAR; PG8_MMA(1, 0, At, B0); PG8_MMA(1, 1, At, B1); PG8_BAR; PG8_SCHED;
	s_add_i32 s58, s75, s62
	v_lshl_add_u64 v[168:169], v[168:169], 0, s[34:35]
	s_mov_b32 m0, s58
	ds_read_b128 v[202:205], v158 offset:49152
	ds_read_b128 v[206:209], v158 offset:50176
	ds_read_b128 v[214:217], v158 offset:51200
	ds_read_b128 v[218:221], v158 offset:52224
	ds_read_b128 v[222:225], v158 offset:53248
	ds_read_b128 v[226:229], v158 offset:54272
	ds_read_b128 v[230:233], v158 offset:55296
	ds_read_b128 v[234:237], v158 offset:56320
	global_load_lds_dwordx4 v[168:169], off
	s_add_i32 m0, s58, 0x2000
	s_add_u32 s56, s56, 0x80080
	v_lshl_add_u64 v[168:169], v[238:239], 0, s[34:35]
	s_addc_u32 s57, s57, 0
	s_add_i32 s58, s76, s62
	global_load_lds_dwordx4 v[168:169], off
	v_lshl_add_u64 v[168:169], s[56:57], 0, v[0:1]
	s_mov_b32 m0, s58
	s_nop 0
	global_load_lds_dwordx4 v[168:169], off
	v_lshl_add_u64 v[168:169], s[56:57], 0, v[130:131]
	s_add_i32 m0, s58, 0x2000
	s_nop 0
	global_load_lds_dwordx4 v[168:169], off
	v_lshl_add_u64 v[168:169], v[240:241], 0, s[34:35]
	s_mov_b32 m0, s67
	s_nop 0
	global_load_lds_dwordx4 v[168:169], off
	v_lshl_add_u64 v[168:169], v[242:243], 0, s[34:35]
	s_mov_b32 m0, s68
	s_nop 0
	global_load_lds_dwordx4 v[168:169], off
	s_waitcnt vmcnt(8)
	s_waitcnt lgkmcnt(0)
	s_setprio 1
	s_barrier
	v_mfma_f32_16x16x32_bf16 v[62:65], v[152:155], v[202:205], v[62:65]
	v_mfma_f32_16x16x32_bf16 v[58:61], v[164:167], v[202:205], v[58:61]
	v_mfma_f32_16x16x32_bf16 v[46:49], v[152:155], v[214:217], v[46:49]
	v_mfma_f32_16x16x32_bf16 v[42:45], v[164:167], v[214:217], v[42:45]
	v_mfma_f32_16x16x32_bf16 v[30:33], v[152:155], v[222:225], v[30:33]
	v_mfma_f32_16x16x32_bf16 v[26:29], v[164:167], v[222:225], v[26:29]
	v_mfma_f32_16x16x32_bf16 v[14:17], v[152:155], v[230:233], v[14:17]
	v_mfma_f32_16x16x32_bf16 v[10:13], v[164:167], v[230:233], v[10:13]
	v_mfma_f32_16x16x32_bf16 v[62:65], v[160:163], v[206:209], v[62:65]
	v_mfma_f32_16x16x32_bf16 v[58:61], v[182:185], v[206:209], v[58:61]
	v_mfma_f32_16x16x32_bf16 v[46:49], v[160:163], v[218:221], v[46:49]
	v_mfma_f32_16x16x32_bf16 v[42:45], v[182:185], v[218:221], v[42:45]
	v_mfma_f32_16x16x32_bf16 v[30:33], v[160:163], v[226:229], v[30:33]
	v_mfma_f32_16x16x32_bf16 v[26:29], v[182:185], v[226:229], v[26:29]
	v_mfma_f32_16x16x32_bf16 v[14:17], v[160:163], v[234:237], v[14:17]
	v_mfma_f32_16x16x32_bf16 v[10:13], v[182:185], v[234:237], v[10:13]
	s_setprio 0
	s_setprio 1
	v_mfma_f32_16x16x32_bf16 v[54:57], v[186:189], v[202:205], v[54:57]
	v_mfma_f32_16x16x32_bf16 v[50:53], v[194:197], v[202:205], v[50:53]
	v_mfma_f32_16x16x32_bf16 v[38:41], v[186:189], v[214:217], v[38:41]
	v_mfma_f32_16x16x32_bf16 v[34:37], v[194:197], v[214:217], v[34:37]
	v_mfma_f32_16x16x32_bf16 v[22:25], v[186:189], v[222:225], v[22:25]
	v_mfma_f32_16x16x32_bf16 v[18:21], v[194:197], v[222:225], v[18:21]
	v_mfma_f32_16x16x32_bf16 v[6:9], v[186:189], v[230:233], v[6:9]
	v_mfma_f32_16x16x32_bf16 v[2:5], v[194:197], v[230:233], v[2:5]
	v_mfma_f32_16x16x32_bf16 v[54:57], v[190:193], v[206:209], v[54:57]
	v_mfma_f32_16x16x32_bf16 v[50:53], v[198:201], v[206:209], v[50:53]
	v_mfma_f32_16x16x32_bf16 v[38:41], v[190:193], v[218:221], v[38:41]
	v_mfma_f32_16x16x32_bf16 v[34:37], v[198:201], v[218:221], v[34:37]
	v_mfma_f32_16x16x32_bf16 v[22:25], v[190:193], v[226:229], v[22:25]
	v_mfma_f32_16x16x32_bf16 v[18:21], v[198:201], v[226:229], v[18:21]
	v_mfma_f32_16x16x32_bf16 v[6:9], v[190:193], v[234:237], v[6:9]
	v_mfma_f32_16x16x32_bf16 v[2:5], v[198:201], v[234:237], v[2:5]
	s_setprio 0
	s_add_i32 s74, s74, 2
	s_add_u32 s72, s72, 0x100
	s_addc_u32 s73, s73, 0
	s_add_u32 s40, s40, 0x100
	s_addc_u32 s41, s41, 0
	s_cmp_gt_u32 s74, 29
	s_cbranch_scc1 .Lg1_exit_bar
	s_add_u32 s56, s40, 0xfff80080
	s_addc_u32 s57, s41, -1
	s_add_i32 s75, 0, 0x10000
	s_cmp_eq_u32 s74, 28
	s_cselect_b32 s59, s2, s57
	s_cselect_b32 s58, s3, s56
	s_cselect_b32 s57, s49, s73
	s_cselect_b32 s56, s51, s72
	s_add_i32 s78, 0, 0x14000
	s_branch .Lg1_head_bar
.Lg1_exit_bar:
	s_barrier
	s_and_b64 vcc, exec, s[44:45]
	s_cbranch_vccz .LBB0_421
	s_barrier
